# v14: natural-order V rows in LDS, P-packing permlane swaps removed (loop + tail)
# speedup vs baseline: 1.0069x; 1.0020x over previous
.LBB0_525:
	s_mul_i32 s7, s7, 0x9800
	s_mul_hi_u32 s8, s6, 0x9800
	s_and_b32 s4, s10, 15
	s_add_i32 s8, s8, s7
	s_mul_i32 s6, s6, 0x9800
	s_add_u32 s6, s50, s6
	s_addc_u32 s7, s51, s8
	s_lshl_b32 s4, s4, 8
	s_add_u32 s48, s6, s4
	s_addc_u32 s49, s7, 0
	s_lshl_b32 s4, s11, 2
	s_bfe_u32 s6, s10, 0x20002
	s_or_b32 s26, s4, s6
	v_mbcnt_lo_u32_b32 v76, -1, 0
	v_mbcnt_hi_u32_b32 v76, -1, v76
	s_mul_i32 s6, s26, 0x210000
	v_add_u32_e32 v54, s39, v76
	v_ashrrev_i32_e32 v16, 4, v54
	s_mul_hi_i32 s4, s26, 0x210000
	s_add_u32 s40, s52, s6
	v_lshlrev_b32_e32 v22, 3, v76
	v_add_u32_e32 v18, 32, v16
	s_addc_u32 s41, s53, s4
	v_and_b32_e32 v0, 0x78, v22
	v_ashrrev_i32_e32 v17, 31, v16
	v_ashrrev_i32_e32 v19, 31, v18
	s_add_u32 s42, s54, s6
	v_lshlrev_b32_e32 v23, 1, v0
	v_lshlrev_b64 v[48:49], 8, v[16:17]
	v_lshlrev_b64 v[8:9], 8, v[18:19]
	s_addc_u32 s43, s55, s4
	v_or_b32_e32 v52, v48, v23
	v_mov_b32_e32 v53, v49
	v_or_b32_e32 v8, v8, v23
	v_lshl_add_u64 v[0:1], s[42:43], 0, v[52:53]
	v_lshl_add_u64 v[4:5], s[42:43], 0, v[8:9]
	v_lshl_add_u64 v[10:11], s[40:41], 0, v[52:53]
	v_lshl_add_u64 v[12:13], s[40:41], 0, v[8:9]
	global_load_dwordx4 v[0:3], v[0:1], off
	s_nop 0
	global_load_dwordx4 v[4:7], v[4:5], off
	s_nop 0
	global_load_dwordx4 v[8:11], v[10:11], off
	s_nop 0
	global_load_dwordx4 v[12:15], v[12:13], off
	v_ashrrev_i32_e32 v55, 1, v54
	s_movk_i32 s4, 0xffe0
	v_bfe_u32 v97, v76, 5, 1
	v_bfi_b32 v17, s4, v55, v76
	v_mov_b64_e32 v[20:21], s[48:49]
	v_mad_i64_i32 v[20:21], s[6:7], v17, s21, v[20:21]
	v_lshlrev_b32_e32 v50, 4, v97
	v_mov_b32_e32 v51, v96
	v_lshl_add_u64 v[20:21], v[20:21], 0, v[50:51]
	global_load_dwordx4 v[118:121], v[20:21], off
	global_load_dwordx4 v[114:117], v[20:21], off offset:32
	global_load_dwordx4 v[126:129], v[20:21], off offset:64
	global_load_dwordx4 v[122:125], v[20:21], off offset:96
	global_load_dwordx4 v[110:113], v[20:21], off offset:128
	global_load_dwordx4 v[106:109], v[20:21], off offset:160
	global_load_dwordx4 v[102:105], v[20:21], off offset:192
	global_load_dwordx4 v[98:101], v[20:21], off offset:224
	v_bfe_u32 v17, v22, 5, 2
	v_and_b32_e32 v22, 0xfffff0, v16
	v_lshlrev_b32_e32 v24, 1, v16
	v_lshrrev_b32_e32 v25, 1, v16
	v_and_b32_e32 v26, 3, v16
	v_and_b32_e32 v19, 0xf0, v54
	v_lshlrev_b32_e32 v16, 8, v16
	v_and_or_b32 v22, v24, 8, v22
	v_bfe_u32 v24, v24, 1, 3
	v_and_b32_e32 v26, 0xfffff0, v18
	v_lshlrev_b32_e32 v27, 1, v18
	v_bitop3_b32 v16, v23, v16, v19 bitop3:0xde
	v_lshlrev_b32_e32 v18, 8, v18
	v_and_b32_e32 v22, 12, v25
	v_and_or_b32 v26, v27, 8, v26
	v_add_u32_e32 v188, 0, v16
	v_bitop3_b32 v16, v18, v23, v19 bitop3:0xf6
	v_or_b32_e32 v18, v22, v17
	v_and_or_b32 v19, v25, 12, 16
	v_and_b32_e32 v25, 48, v23
	v_lshlrev_b32_e32 v24, 6, v24
	v_add_u32_e32 v189, 0, v16
	v_lshlrev_b32_e32 v16, 9, v18
	v_or_b32_e32 v17, v19, v17
	v_or3_b32 v16, v16, v24, v25
	v_lshlrev_b32_e32 v17, 9, v17
	v_and_b32_e32 v180, 31, v76
	v_lshlrev_b32_e32 v51, 4, v76
	v_or3_b32 v17, v17, v24, v25
	v_add_u32_e32 v190, 0, v16
	v_add_u32_e32 v191, 0, v17
	s_waitcnt vmcnt(0)
	s_add_i32 s4, 0, 0x10000
	s_mov_b64 s[6:7], 0x6000
	v_and_b32_e32 v181, 0xffffffe0, v55
	v_and_b32_e32 v77, 63, v76
	s_mov_b32 s8, s5
	s_mov_b32 s9, s5
	s_mov_b32 s10, s5
	s_mov_b32 s11, s5
	s_mov_b32 s12, s5
	s_waitcnt vmcnt(0)
	ds_write_b128 v190, v[0:3]
	s_waitcnt vmcnt(10)
	ds_write_b128 v191, v[4:7]
	s_waitcnt vmcnt(9)
	ds_write_b128 v188, v[8:11] offset:32768
	s_waitcnt vmcnt(8)
	ds_write_b128 v189, v[12:15] offset:32768
	v_lshlrev_b32_e32 v12, 8, v180
	v_and_b32_e32 v13, 0xf0, v51
	v_bitop3_b32 v0, v50, v12, v13 bitop3:0xde
	v_add_u32_e32 v192, 0, v0
	s_waitcnt lgkmcnt(0)
	s_barrier
	ds_read_b128 v[0:3], v192 offset:32768
	ds_read_b128 v[4:7], v192 offset:40960
	s_waitcnt vmcnt(7) lgkmcnt(1)
	v_mfma_f32_32x32x16_bf16 v[16:31], v[0:3], v[118:121], 0
	v_or_b32_e32 v0, 32, v50
	v_bitop3_b32 v0, v0, v12, v13 bitop3:0xde
	v_add_u32_e32 v200, 0, v0
	v_lshl_add_u64 v[8:9], v[52:53], 0, s[6:7]
	v_lshl_add_u64 v[10:11], s[42:43], 0, v[8:9]
	v_lshlrev_b32_e32 v14, 3, v77
	v_and_b32_e32 v15, 0xc0, v51
	s_waitcnt lgkmcnt(0)
	v_mfma_f32_32x32x16_bf16 v[32:47], v[4:7], v[118:121], 0
	ds_read_b128 v[0:3], v200 offset:32768
	ds_read_b128 v[4:7], v200 offset:40960
	s_mov_b32 s6, s5
	s_mov_b32 s7, s5
	s_mov_b32 s13, s5
	s_mov_b32 s14, s5
	s_mov_b32 s15, s5
	s_mov_b32 s16, s5
	s_waitcnt vmcnt(6) lgkmcnt(1)
	v_mfma_f32_32x32x16_bf16 v[16:31], v[0:3], v[114:117], v[16:31]
	v_or_b32_e32 v0, 64, v50
	v_bitop3_b32 v0, v0, v12, v13 bitop3:0xde
	v_add_u32_e32 v199, 0, v0
	s_mov_b32 s17, s5
	s_mov_b32 s18, s5
	s_mov_b32 s19, s5
	s_cmp_lg_u32 0, -1
	s_waitcnt lgkmcnt(0)
	v_mfma_f32_32x32x16_bf16 v[32:47], v[4:7], v[114:117], v[32:47]
	ds_read_b128 v[0:3], v199 offset:32768
	ds_read_b128 v[4:7], v199 offset:40960
	s_cselect_b32 s27, 0, 0
	v_lshlrev_b32_e32 v183, 2, v97
	v_mov_b32_e32 v185, 0
	s_waitcnt vmcnt(5) lgkmcnt(1)
	v_mfma_f32_32x32x16_bf16 v[16:31], v[0:3], v[126:129], v[16:31]
	v_or_b32_e32 v0, 0x60, v50
	v_bitop3_b32 v0, v0, v12, v13 bitop3:0xde
	v_add_u32_e32 v198, 0, v0
	s_waitcnt lgkmcnt(0)
	v_mfma_f32_32x32x16_bf16 v[32:47], v[4:7], v[126:129], v[32:47]
	ds_read_b128 v[0:3], v198 offset:32768
	ds_read_b128 v[4:7], v198 offset:40960
	s_waitcnt vmcnt(4) lgkmcnt(1)
	v_mfma_f32_32x32x16_bf16 v[16:31], v[0:3], v[122:125], v[16:31]
	v_or_b32_e32 v0, 0x80, v50
	v_bitop3_b32 v0, v0, v12, v13 bitop3:0xde
	v_add_u32_e32 v195, 0, v0
	s_waitcnt lgkmcnt(0)
	v_mfma_f32_32x32x16_bf16 v[32:47], v[4:7], v[122:125], v[32:47]
	ds_read_b128 v[0:3], v195 offset:32768
	ds_read_b128 v[4:7], v195 offset:40960
	s_waitcnt vmcnt(3) lgkmcnt(1)
	v_mfma_f32_32x32x16_bf16 v[16:31], v[0:3], v[110:113], v[16:31]
	v_or_b32_e32 v0, 0xa0, v50
	v_bitop3_b32 v0, v0, v12, v13 bitop3:0xde
	v_add_u32_e32 v193, 0, v0
	ds_read_b128 v[0:3], v193 offset:32768
	s_waitcnt lgkmcnt(1)
	v_mfma_f32_32x32x16_bf16 v[32:47], v[4:7], v[110:113], v[32:47]
	v_and_b32_e32 v4, 0x3fffffc0, v54
	v_lshl_add_u32 v78, v4, 2, s4
	ds_read_b128 v[4:7], v193 offset:40960
	s_mov_b32 s4, s5
	v_add_u32_e32 v182, v78, v50
	v_lshl_add_u32 v184, v180, 2, v78
	s_waitcnt vmcnt(2) lgkmcnt(1)
	v_mfma_f32_32x32x16_bf16 v[16:31], v[0:3], v[106:109], v[16:31]
	v_lshl_add_u64 v[0:1], v[52:53], 0, s[68:69]
	v_lshl_add_u64 v[2:3], s[42:43], 0, v[0:1]
	v_lshl_add_u64 v[0:1], s[40:41], 0, v[0:1]
	global_load_dwordx4 v[54:57], v[2:3], off
	global_load_dwordx4 v[58:61], v[10:11], off
	v_lshl_add_u64 v[2:3], s[40:41], 0, v[8:9]
	global_load_dwordx4 v[62:65], v[0:1], off
	global_load_dwordx4 v[66:69], v[2:3], off
	v_or_b32_e32 v0, 0xc0, v50
	v_bitop3_b32 v0, v0, v12, v13 bitop3:0xde
	v_add_u32_e32 v202, 0, v0
	ds_read_b128 v[0:3], v202 offset:32768
	v_lshlrev_b32_e32 v9, 1, v76
	v_and_or_b32 v8, v14, 24, v15
	s_waitcnt lgkmcnt(1)
	v_mfma_f32_32x32x16_bf16 v[32:47], v[4:7], v[106:109], v[32:47]
	v_and_b32_e32 v4, 32, v9
	v_and_b32_e32 v5, 0x100, v14
	v_or3_b32 v51, v8, v4, v5
	ds_read_b128 v[4:7], v202 offset:40960
	v_add_u32_e32 v187, s27, v51
	s_waitcnt vmcnt(5) lgkmcnt(1)
	v_mfma_f32_32x32x16_bf16 v[16:31], v[0:3], v[102:105], v[16:31]
	v_or_b32_e32 v0, 0xe0, v50
	v_bitop3_b32 v0, v0, v12, v13 bitop3:0xde
	v_add_u32_e32 v201, 0, v0
	ds_read_b128 v[0:3], v201 offset:32768
	ds_read_b128 v[70:73], v201 offset:40960
	s_waitcnt lgkmcnt(2)
	v_mfma_f32_32x32x16_bf16 v[32:47], v[4:7], v[102:105], v[32:47]
	s_waitcnt vmcnt(4) lgkmcnt(1)
	v_mfma_f32_32x32x16_bf16 v[16:31], v[0:3], v[98:101], v[16:31]
	v_mov_b64_e32 v[0:1], s[4:5]
	v_mov_b64_e32 v[2:3], s[6:7]
	v_mov_b64_e32 v[4:5], s[8:9]
	v_mov_b64_e32 v[6:7], s[10:11]
	v_mov_b64_e32 v[8:9], s[12:13]
	v_mov_b64_e32 v[10:11], s[14:15]
	v_mov_b64_e32 v[12:13], s[16:17]
	s_waitcnt lgkmcnt(0)
	v_mfma_f32_32x32x16_bf16 v[32:47], v[70:73], v[98:101], v[32:47]
	s_nop 2
	v_max_f32_e32 v70, v17, v17
	v_max_f32_e32 v71, v16, v16
	v_max_f32_e32 v70, v71, v70
	v_max3_f32 v70, v70, v18, v19
	v_max3_f32 v70, v70, v20, v21
	v_max3_f32 v70, v70, v22, v23
	v_max3_f32 v70, v70, v24, v25
	v_max3_f32 v70, v70, v26, v27
	v_max3_f32 v70, v70, v28, v29
	v_max3_f32 v70, v70, v30, v31
	v_max3_f32 v70, v70, v32, v33
	v_max3_f32 v70, v70, v34, v35
	v_max3_f32 v70, v70, v36, v37
	v_max3_f32 v70, v70, v38, v39
	v_max3_f32 v70, v70, v40, v41
	v_max3_f32 v70, v70, v42, v43
	v_mov_b64_e32 v[14:15], s[18:19]
	v_max3_f32 v70, v70, v44, v45
	s_mov_b64 s[6:7], 0x8000
	v_max3_f32 v79, v70, v46, v47
	v_lshl_add_u64 v[70:71], v[52:53], 0, s[6:7]
	s_mov_b64 s[6:7], 0xa000
	v_lshl_add_u64 v[72:73], s[42:43], 0, v[70:71]
	v_lshl_add_u64 v[52:53], v[52:53], 0, s[6:7]
	v_lshl_add_u64 v[70:71], s[40:41], 0, v[70:71]
	v_lshl_add_u64 v[74:75], s[42:43], 0, v[52:53]
	global_load_dwordx4 v[130:133], v[72:73], off
	global_load_dwordx4 v[138:141], v[74:75], off
	v_lshl_add_u64 v[52:53], s[40:41], 0, v[52:53]
	global_load_dwordx4 v[134:137], v[70:71], off
	global_load_dwordx4 v[142:145], v[52:53], off
	v_mov_b32_e32 v80, v79
	s_nop 1
	v_permlane32_swap_b32_e32 v79, v80
	v_max_f32_e32 v52, v80, v80
	v_max_f32_e32 v53, v79, v79
	v_max_f32_e32 v52, v53, v52
	v_add_f32_e32 v53, 0x7149f2ca, v52
	v_max_f32_e32 v52, 0xf149f2ca, v52
	v_cmp_ge_f32_e32 vcc, s92, v53
	v_sub_f32_e32 v53, 0xf149f2ca, v52
	v_mul_f32_e32 v53, 0x3e0293ee, v53
	v_exp_f32_e32 v53, v53
	s_cmp_eq_u64 vcc, exec
	s_cselect_b64 vcc, -1, 0
	s_waitcnt vmcnt(4)
	v_cndmask_b32_e64 v203, v53, 1.0, vcc
	v_mov_b32_e32 v53, 0xf149f2ca
	v_cndmask_b32_e32 v170, v52, v53, vcc
	v_mul_f32_e32 v52, 0xbe0293ee, v170
	v_fmamk_f32 v16, v16, 0x3e0293ee, v52
	v_exp_f32_e32 v163, v16
	v_fmamk_f32 v16, v17, 0x3e0293ee, v52
	v_exp_f32_e32 v177, v16
	v_fmamk_f32 v16, v18, 0x3e0293ee, v52
	v_exp_f32_e32 v164, v16
	v_fmamk_f32 v16, v19, 0x3e0293ee, v52
	v_exp_f32_e32 v207, v16
	v_fmamk_f32 v16, v20, 0x3e0293ee, v52
	v_exp_f32_e32 v176, v16
	v_fmamk_f32 v16, v21, 0x3e0293ee, v52
	v_exp_f32_e32 v210, v16
	v_fmamk_f32 v16, v22, 0x3e0293ee, v52
	v_exp_f32_e32 v165, v16
	v_fmamk_f32 v16, v23, 0x3e0293ee, v52
	v_exp_f32_e32 v175, v16
	v_fmamk_f32 v16, v24, 0x3e0293ee, v52
	v_exp_f32_e32 v166, v16
	v_fmamk_f32 v16, v25, 0x3e0293ee, v52
	v_exp_f32_e32 v173, v16
	v_fmamk_f32 v16, v26, 0x3e0293ee, v52
	v_exp_f32_e32 v167, v16
	v_fmamk_f32 v16, v27, 0x3e0293ee, v52
	v_exp_f32_e32 v174, v16
	v_fmamk_f32 v16, v28, 0x3e0293ee, v52
	v_exp_f32_e32 v168, v16
	v_fmamk_f32 v16, v29, 0x3e0293ee, v52
	v_exp_f32_e32 v171, v16
	v_fmamk_f32 v16, v30, 0x3e0293ee, v52
	v_pk_fma_f32 v[146:147], v[46:47], s[88:89], v[52:53] op_sel_hi:[1,0,0]
	v_pk_fma_f32 v[152:153], v[44:45], s[88:89], v[52:53] op_sel_hi:[1,0,0]
	v_pk_fma_f32 v[156:157], v[42:43], s[88:89], v[52:53] op_sel_hi:[1,0,0]
	v_pk_fma_f32 v[148:149], v[40:41], s[88:89], v[52:53] op_sel_hi:[1,0,0]
	v_pk_fma_f32 v[150:151], v[38:39], s[88:89], v[52:53] op_sel_hi:[1,0,0]
	v_pk_fma_f32 v[154:155], v[36:37], s[88:89], v[52:53] op_sel_hi:[1,0,0]
	v_pk_fma_f32 v[158:159], v[34:35], s[88:89], v[52:53] op_sel_hi:[1,0,0]
	v_pk_fma_f32 v[160:161], v[32:33], s[88:89], v[52:53] op_sel_hi:[1,0,0]
	v_exp_f32_e32 v169, v16
	v_fmac_f32_e32 v52, 0x3e0293ee, v31
	v_mov_b32_e32 v16, 0x210000
	v_exp_f32_e32 v172, v52
	v_mad_i64_i32 v[16:17], s[6:7], s26, v16, v[48:49]
	v_and_b32_e32 v18, 15, v76
	s_addk_i32 s27, 0x4000
	v_lshl_or_b32 v16, v18, 4, v16
	s_waitcnt vmcnt(7)
	ds_write_b128 v190, v[54:57] offset:16384
	s_waitcnt vmcnt(6)
	ds_write_b128 v191, v[58:61] offset:16384
	s_waitcnt vmcnt(5)
	ds_write_b128 v188, v[62:65] offset:49152
	s_waitcnt vmcnt(4)
	ds_write_b128 v189, v[66:69] offset:49152
	v_add_u32_e32 v186, s27, v51
	v_lshl_add_u64 v[178:179], s[46:47], 0, v[16:17]
	v_mov_b64_e32 v[62:63], v[14:15]
	v_mov_b64_e32 v[46:47], v[14:15]
	v_mov_b64_e32 v[30:31], v[14:15]
	v_cmp_gt_u32_e64 s[40:41], 32, v77
	v_mov_b64_e32 v[60:61], v[12:13]
	v_mov_b64_e32 v[58:59], v[10:11]
	v_mov_b64_e32 v[56:57], v[8:9]
	v_mov_b64_e32 v[54:55], v[6:7]
	v_mov_b64_e32 v[52:53], v[4:5]
	v_mov_b64_e32 v[50:51], v[2:3]
	v_mov_b64_e32 v[48:49], v[0:1]
	v_mov_b64_e32 v[44:45], v[12:13]
	v_mov_b64_e32 v[42:43], v[10:11]
	v_mov_b64_e32 v[40:41], v[8:9]
	v_mov_b64_e32 v[38:39], v[6:7]
	v_mov_b64_e32 v[36:37], v[4:5]
	v_mov_b64_e32 v[34:35], v[2:3]
	v_mov_b64_e32 v[32:33], v[0:1]
	v_mov_b64_e32 v[28:29], v[12:13]
	v_mov_b64_e32 v[26:27], v[10:11]
	v_mov_b64_e32 v[24:25], v[8:9]
	v_mov_b64_e32 v[22:23], v[6:7]
	v_mov_b64_e32 v[20:21], v[4:5]
	v_mov_b64_e32 v[18:19], v[2:3]
	v_mov_b64_e32 v[16:17], v[0:1]
	s_waitcnt lgkmcnt(0)
	s_barrier
	v_readfirstlane_b32 s66, v178
	v_readfirstlane_b32 s67, v179
	s_nop 3
	v_subrev_u32_e32 v178, s66, v178
	v_add_u32_e32 v179, 0x2000, v178
	s_add_u32 s98, s66, 0xfef7a000
	s_addc_u32 s99, s67, -1
	s_add_u32 s66, s66, 0xffffa000
	s_addc_u32 s67, s67, -1
.LBB0_526:
	ds_read_b128 v[64:67], v192 offset:49152
	ds_read_b128 v[68:71], v192 offset:57344
	ds_read_b128 v[232:235], v200 offset:49152
	ds_read_b128 v[236:239], v200 offset:57344
	ds_read_b128 v[250:253], v199 offset:49152
	ds_read_b128 v[244:247], v199 offset:57344
	ds_read_b128 v[212:215], v198 offset:49152
	ds_read_b128 v[216:219], v198 offset:57344
	v_add_f32_e32 v162, 0, v163
	v_add_f32_e32 v162, v177, v162
	s_waitcnt lgkmcnt(6)
	v_mfma_f32_32x32x16_bf16 v[80:95], v[64:67], v[118:121], 0
	v_add_f32_e32 v162, v164, v162
	v_add_f32_e32 v162, v207, v162
	v_add_f32_e32 v162, v176, v162
	v_add_f32_e32 v162, v210, v162
	v_mfma_f32_32x32x16_bf16 v[64:79], v[68:71], v[118:121], 0
	v_add_f32_e32 v162, v165, v162
	v_add_f32_e32 v162, v175, v162
	v_add_f32_e32 v162, v166, v162
	v_add_f32_e32 v162, v173, v162
	v_add_f32_e32 v162, v167, v162
	s_waitcnt lgkmcnt(4)
	v_mfma_f32_32x32x16_bf16 v[80:95], v[232:235], v[114:117], v[80:95]
	ds_read_b128 v[232:235], v195 offset:49152
	v_add_f32_e32 v162, v174, v162
	v_exp_f32_e32 v160, v160
	v_add_f32_e32 v162, v168, v162
	v_exp_f32_e32 v161, v161
	v_mfma_f32_32x32x16_bf16 v[64:79], v[236:239], v[114:117], v[64:79]
	ds_read_b128 v[236:239], v195 offset:57344
	v_add_f32_e32 v162, v171, v162
	v_exp_f32_e32 v158, v158
	v_add_f32_e32 v162, v169, v162
	v_exp_f32_e32 v159, v159
	s_waitcnt lgkmcnt(4)
	v_mfma_f32_32x32x16_bf16 v[80:95], v[250:253], v[126:129], v[80:95]
	ds_read_b128 v[250:253], v193 offset:49152
	v_add_f32_e32 v162, v172, v162
	v_exp_f32_e32 v154, v154
	v_add_f32_e32 v162, v160, v162
	v_exp_f32_e32 v155, v155
	v_mfma_f32_32x32x16_bf16 v[64:79], v[244:247], v[126:129], v[64:79]
	ds_read_b128 v[244:247], v193 offset:57344
	v_add_f32_e32 v162, v161, v162
	v_exp_f32_e32 v150, v150
	v_add_f32_e32 v162, v158, v162
	v_exp_f32_e32 v151, v151
	s_waitcnt lgkmcnt(4)
	v_mfma_f32_32x32x16_bf16 v[80:95], v[212:215], v[122:125], v[80:95]
	ds_read_b128 v[212:215], v202 offset:49152
	v_add_f32_e32 v162, v159, v162
	v_exp_f32_e32 v148, v148
	v_add_f32_e32 v162, v154, v162
	v_exp_f32_e32 v149, v149
	v_mfma_f32_32x32x16_bf16 v[64:79], v[216:219], v[122:125], v[64:79]
	ds_read_b128 v[216:219], v202 offset:57344
	v_add_f32_e32 v162, v155, v162
	v_exp_f32_e32 v156, v156
	v_add_f32_e32 v162, v150, v162
	v_exp_f32_e32 v157, v157
	s_waitcnt lgkmcnt(4)
	v_mfma_f32_32x32x16_bf16 v[80:95], v[232:235], v[110:113], v[80:95]
	ds_read_b128 v[232:235], v201 offset:49152
	v_add_f32_e32 v162, v151, v162
	v_exp_f32_e32 v152, v152
	v_add_f32_e32 v162, v148, v162
	v_exp_f32_e32 v153, v153
	v_mfma_f32_32x32x16_bf16 v[64:79], v[236:239], v[110:113], v[64:79]
	ds_read_b128 v[236:239], v201 offset:57344
	v_add_f32_e32 v162, v149, v162
	v_exp_f32_e32 v146, v146
	v_add_f32_e32 v162, v156, v162
	v_exp_f32_e32 v147, v147
	s_waitcnt lgkmcnt(4)
	v_mfma_f32_32x32x16_bf16 v[80:95], v[250:253], v[106:109], v[80:95]
	v_add_f32_e32 v162, v157, v162
	v_add_f32_e32 v162, v152, v162
	v_add_f32_e32 v162, v153, v162
	v_add_f32_e32 v162, v146, v162
	v_add_f32_e32 v204, v147, v162
	v_mov_b32_e32 v205, v204
	v_mfma_f32_32x32x16_bf16 v[64:79], v[244:247], v[106:109], v[64:79]
	s_nop 0
	v_permlane32_swap_b32_e32 v204, v205
	v_cvt_pk_bf16_f32 v162, v163, v177
	v_cvt_pk_bf16_f32 v163, v164, v207
	v_cvt_pk_bf16_f32 v164, v176, v210
	s_waitcnt lgkmcnt(2)
	v_mfma_f32_32x32x16_bf16 v[80:95], v[212:215], v[102:105], v[80:95]
	v_cvt_pk_bf16_f32 v165, v165, v175
	v_cvt_pk_bf16_f32 v166, v166, v173
	v_cvt_pk_bf16_f32 v167, v167, v174
	v_cvt_pk_bf16_f32 v168, v168, v171
	v_mfma_f32_32x32x16_bf16 v[64:79], v[216:219], v[102:105], v[64:79]
	v_cvt_pk_bf16_f32 v169, v169, v172
	v_cvt_pk_bf16_f32 v172, v160, v161
	v_cvt_pk_bf16_f32 v173, v158, v159
	v_cvt_pk_bf16_f32 v174, v154, v155
	ds_read_b64_tr_b16 v[210:211], v187 offset:0x0
	ds_read_b64_tr_b16 v[212:213], v187 offset:0x800
	ds_read_b64_tr_b16 v[214:215], v187 offset:0x200
	ds_read_b64_tr_b16 v[216:217], v187 offset:0xa00
	ds_read_b64_tr_b16 v[218:219], v187 offset:0x400
	ds_read_b64_tr_b16 v[220:221], v187 offset:0xc00
	ds_read_b64_tr_b16 v[222:223], v187 offset:0x600
	ds_read_b64_tr_b16 v[224:225], v187 offset:0xe00
	s_waitcnt lgkmcnt(8)
	v_mfma_f32_32x32x16_bf16 v[80:95], v[232:235], v[98:101], v[80:95]
	v_cvt_pk_bf16_f32 v175, v150, v151
	v_cvt_pk_bf16_f32 v206, v148, v149
	v_cvt_pk_bf16_f32 v207, v156, v157
	v_mfma_f32_32x32x16_bf16 v[64:79], v[236:239], v[98:101], v[64:79]
	v_cvt_pk_bf16_f32 v208, v152, v153
	v_cvt_pk_bf16_f32 v209, v146, v147
	s_waitcnt vmcnt(0)
	ds_write_b128 v188, v[134:137] offset:32768
	ds_write_b128 v189, v[142:145] offset:32768
	global_load_dwordx4 v[146:149], v178, s[66:67]
	global_load_dwordx4 v[150:153], v179, s[66:67]
	global_load_dwordx4 v[154:157], v178, s[98:99]
	global_load_dwordx4 v[158:161], v179, s[98:99]
	s_add_u32 s66, s66, 0x4000
	s_addc_u32 s67, s67, 0
	s_add_u32 s98, s98, 0x4000
	s_addc_u32 s99, s99, 0
	s_waitcnt lgkmcnt(6)
	v_mfma_f32_32x32x16_bf16 v[0:15], v[162:165], v[210:213], v[0:15]
	ds_read_b64_tr_b16 v[210:211], v187 offset:0x1000
	ds_read_b64_tr_b16 v[212:213], v187 offset:0x1800
	v_max_f32_e32 v240, v80, v81
	v_max3_f32 v240, v240, v82, v83
	v_max3_f32 v240, v240, v84, v85
	v_max3_f32 v240, v240, v86, v87
	v_max3_f32 v240, v240, v88, v89
	v_mfma_f32_32x32x16_bf16 v[48:63], v[162:165], v[214:217], v[48:63]
	ds_read_b64_tr_b16 v[214:215], v187 offset:0x1200
	ds_read_b64_tr_b16 v[216:217], v187 offset:0x1a00
	v_max3_f32 v240, v240, v90, v91
	v_max3_f32 v240, v240, v92, v93
	v_max3_f32 v240, v240, v94, v95
	v_max3_f32 v240, v240, v64, v65
	v_max3_f32 v240, v240, v66, v67
	v_max3_f32 v240, v240, v68, v69
	s_waitcnt lgkmcnt(6)
	v_mfma_f32_32x32x16_bf16 v[32:47], v[162:165], v[218:221], v[32:47]
	ds_read_b64_tr_b16 v[218:219], v187 offset:0x1400
	ds_read_b64_tr_b16 v[220:221], v187 offset:0x1c00
	v_max3_f32 v240, v240, v70, v71
	v_max3_f32 v240, v240, v72, v73
	v_max3_f32 v240, v240, v74, v75
	v_max3_f32 v240, v240, v76, v77
	v_max3_f32 v240, v240, v78, v79
	v_mfma_f32_32x32x16_bf16 v[16:31], v[162:165], v[222:225], v[16:31]
	ds_read_b64_tr_b16 v[222:223], v187 offset:0x1600
	ds_read_b64_tr_b16 v[224:225], v187 offset:0x1e00
	v_mov_b32_e32 v241, v240
	s_nop 1
	v_permlane32_swap_b32_e32 v240, v241
	v_max_f32_e32 v240, v240, v241
	v_sub_f32_e32 v241, v240, v170
	v_cmp_ge_f32_e32 vcc, s92, v241
	s_waitcnt lgkmcnt(4)
	v_mfma_f32_32x32x16_bf16 v[0:15], v[166:169], v[210:213], v[0:15]
	ds_read_b64_tr_b16 v[210:211], v187 offset:0x2000
	ds_read_b64_tr_b16 v[212:213], v187 offset:0x2800
	v_max_f32_e32 v240, v170, v240
	v_sub_f32_e32 v241, v170, v240
	v_mul_f32_e32 v241, 0x3e0293ee, v241
	v_exp_f32_e32 v241, v241
	s_cmp_eq_u64 vcc, exec
	s_cselect_b64 s[42:43], -1, 0
	v_mfma_f32_32x32x16_bf16 v[48:63], v[166:169], v[214:217], v[48:63]
	ds_read_b64_tr_b16 v[214:215], v187 offset:0x2200
	ds_read_b64_tr_b16 v[216:217], v187 offset:0x2a00
	v_cndmask_b32_e64 v242, v240, v170, s[42:43]
	v_mul_f32_e32 v243, 0xbe0293ee, v242
	v_fmamk_f32 v80, v80, 0x3e0293ee, v243
	v_fmamk_f32 v81, v81, 0x3e0293ee, v243
	v_fmamk_f32 v82, v82, 0x3e0293ee, v243
	v_fmamk_f32 v83, v83, 0x3e0293ee, v243
	s_waitcnt lgkmcnt(4)
	v_mfma_f32_32x32x16_bf16 v[32:47], v[166:169], v[218:221], v[32:47]
	ds_read_b64_tr_b16 v[218:219], v187 offset:0x2400
	ds_read_b64_tr_b16 v[220:221], v187 offset:0x2c00
	v_fmamk_f32 v84, v84, 0x3e0293ee, v243
	v_fmamk_f32 v85, v85, 0x3e0293ee, v243
	v_fmamk_f32 v86, v86, 0x3e0293ee, v243
	v_fmamk_f32 v87, v87, 0x3e0293ee, v243
	v_fmamk_f32 v88, v88, 0x3e0293ee, v243
	v_fmamk_f32 v89, v89, 0x3e0293ee, v243
	v_mfma_f32_32x32x16_bf16 v[16:31], v[166:169], v[222:225], v[16:31]
	ds_read_b64_tr_b16 v[222:223], v187 offset:0x2600
	ds_read_b64_tr_b16 v[224:225], v187 offset:0x2e00
	v_fmamk_f32 v90, v90, 0x3e0293ee, v243
	v_fmamk_f32 v91, v91, 0x3e0293ee, v243
	v_fmamk_f32 v92, v92, 0x3e0293ee, v243
	v_fmamk_f32 v93, v93, 0x3e0293ee, v243
	v_fmamk_f32 v94, v94, 0x3e0293ee, v243
	v_fmamk_f32 v95, v95, 0x3e0293ee, v243
	s_waitcnt lgkmcnt(4)
	v_mfma_f32_32x32x16_bf16 v[0:15], v[172:175], v[210:213], v[0:15]
	ds_read_b64_tr_b16 v[210:211], v187 offset:0x3000
	ds_read_b64_tr_b16 v[212:213], v187 offset:0x3800
	v_exp_f32_e32 v177, v81
	v_exp_f32_e32 v176, v83
	v_exp_f32_e32 v171, v93
	v_mfma_f32_32x32x16_bf16 v[48:63], v[172:175], v[214:217], v[48:63]
	ds_read_b64_tr_b16 v[214:215], v187 offset:0x3200
	ds_read_b64_tr_b16 v[216:217], v187 offset:0x3a00
	v_exp_f32_e32 v170, v95
	v_exp_f32_e32 v162, v80
	v_exp_f32_e32 v163, v82
	s_waitcnt lgkmcnt(4)
	v_mfma_f32_32x32x16_bf16 v[32:47], v[172:175], v[218:221], v[32:47]
	ds_read_b64_tr_b16 v[218:219], v187 offset:0x3400
	ds_read_b64_tr_b16 v[220:221], v187 offset:0x3c00
	v_exp_f32_e32 v164, v84
	v_exp_f32_e32 v165, v86
	v_exp_f32_e32 v166, v88
	v_mfma_f32_32x32x16_bf16 v[16:31], v[172:175], v[222:225], v[16:31]
	ds_read_b64_tr_b16 v[222:223], v187 offset:0x3600
	ds_read_b64_tr_b16 v[224:225], v187 offset:0x3e00
	v_exp_f32_e32 v167, v90
	v_exp_f32_e32 v168, v92
	v_exp_f32_e32 v169, v94
	s_waitcnt lgkmcnt(4)
	v_mfma_f32_32x32x16_bf16 v[0:15], v[206:209], v[210:213], v[0:15]
	v_exp_f32_e32 v175, v85
	v_exp_f32_e32 v174, v87
	v_exp_f32_e32 v173, v89
	v_mfma_f32_32x32x16_bf16 v[48:63], v[206:209], v[214:217], v[48:63]
	v_exp_f32_e32 v172, v91
	s_waitcnt lgkmcnt(0)
	v_mfma_f32_32x32x16_bf16 v[32:47], v[206:209], v[218:221], v[32:47]
	v_mfma_f32_32x32x16_bf16 v[16:31], v[206:209], v[222:225], v[16:31]
	s_barrier
	v_cndmask_b32_e64 v206, v241, 1.0, s[42:43]
	v_cmp_gt_f32_e32 vcc, 1.0, v206
	ds_write_b128 v190, v[130:133]
	ds_write_b128 v191, v[138:141]
	s_cbranch_vccz .LBB0_530
	s_and_saveexec_b64 s[6:7], s[40:41]
	ds_write_b32 v184, v206 offset:128
	s_or_b64 exec, exec, s[6:7]
	s_waitcnt lgkmcnt(0)
	ds_read_b128 v[210:213], v182 offset:224
	ds_read_b128 v[214:217], v182 offset:192
	ds_read_b128 v[218:221], v182 offset:160
	ds_read_b128 v[222:225], v182 offset:128
	s_waitcnt lgkmcnt(3)
	v_pk_mul_f32 v[14:15], v[14:15], v[212:213]
	s_waitcnt lgkmcnt(2)
	v_pk_mul_f32 v[10:11], v[10:11], v[216:217]
	s_waitcnt lgkmcnt(1)
	v_pk_mul_f32 v[6:7], v[6:7], v[220:221]
	s_waitcnt lgkmcnt(0)
	v_pk_mul_f32 v[2:3], v[2:3], v[224:225]
	v_pk_mul_f32 v[12:13], v[12:13], v[210:211]
	v_pk_mul_f32 v[8:9], v[8:9], v[214:215]
	v_pk_mul_f32 v[4:5], v[4:5], v[218:219]
	v_pk_mul_f32 v[0:1], v[0:1], v[222:223]
	v_pk_mul_f32 v[62:63], v[62:63], v[212:213]
	v_pk_mul_f32 v[58:59], v[58:59], v[216:217]
	v_pk_mul_f32 v[54:55], v[54:55], v[220:221]
	v_pk_mul_f32 v[50:51], v[50:51], v[224:225]
	v_pk_mul_f32 v[60:61], v[60:61], v[210:211]
	v_pk_mul_f32 v[56:57], v[56:57], v[214:215]
	v_pk_mul_f32 v[52:53], v[52:53], v[218:219]
	v_pk_mul_f32 v[48:49], v[48:49], v[222:223]
	v_pk_mul_f32 v[46:47], v[46:47], v[212:213]
	v_pk_mul_f32 v[42:43], v[42:43], v[216:217]
	v_pk_mul_f32 v[38:39], v[38:39], v[220:221]
	v_pk_mul_f32 v[34:35], v[34:35], v[224:225]
	v_pk_mul_f32 v[44:45], v[44:45], v[210:211]
	v_pk_mul_f32 v[40:41], v[40:41], v[214:215]
	v_pk_mul_f32 v[36:37], v[36:37], v[218:219]
	v_pk_mul_f32 v[32:33], v[32:33], v[222:223]
	v_pk_mul_f32 v[30:31], v[30:31], v[212:213]
	v_pk_mul_f32 v[26:27], v[26:27], v[216:217]
	v_pk_mul_f32 v[22:23], v[22:23], v[220:221]
	v_pk_mul_f32 v[18:19], v[18:19], v[224:225]
	v_pk_mul_f32 v[28:29], v[28:29], v[210:211]
	v_pk_mul_f32 v[24:25], v[24:25], v[214:215]
	v_pk_mul_f32 v[20:21], v[20:21], v[218:219]
	v_pk_mul_f32 v[16:17], v[16:17], v[222:223]
.LBB0_530:
	v_fmamk_f32 v217, v64, 0x3e0293ee, v243
	v_fmamk_f32 v218, v65, 0x3e0293ee, v243
	v_fmamk_f32 v219, v66, 0x3e0293ee, v243
	v_fmamk_f32 v220, v67, 0x3e0293ee, v243
	v_fmamk_f32 v221, v68, 0x3e0293ee, v243
	v_fmamk_f32 v210, v69, 0x3e0293ee, v243
	v_fmamk_f32 v211, v70, 0x3e0293ee, v243
	v_fmamk_f32 v212, v71, 0x3e0293ee, v243
	v_fmamk_f32 v213, v72, 0x3e0293ee, v243
	v_fmamk_f32 v214, v73, 0x3e0293ee, v243
	v_fmamk_f32 v215, v74, 0x3e0293ee, v243
	v_fmamk_f32 v216, v75, 0x3e0293ee, v243
	v_fmamk_f32 v209, v76, 0x3e0293ee, v243
	v_fmamk_f32 v222, v77, 0x3e0293ee, v243
	v_fmamk_f32 v223, v78, 0x3e0293ee, v243
	v_fmamk_f32 v208, v79, 0x3e0293ee, v243
	s_waitcnt lgkmcnt(0)
	s_barrier
	ds_read_b128 v[64:67], v192 offset:32768
	ds_read_b128 v[68:71], v192 offset:40960
	ds_read_b128 v[232:235], v200 offset:32768
	ds_read_b128 v[236:239], v200 offset:40960
	ds_read_b128 v[250:253], v199 offset:32768
	ds_read_b128 v[244:247], v199 offset:40960
	ds_read_b128 v[224:227], v198 offset:32768
	ds_read_b128 v[228:231], v198 offset:40960
	v_exp_f32_e32 v248, v208
	v_exp_f32_e32 v249, v209
	s_waitcnt lgkmcnt(6)
	v_mfma_f32_32x32x16_bf16 v[80:95], v[64:67], v[118:121], 0
	v_exp_f32_e32 v217, v217
	v_add_f32_e32 v208, 0, v162
	v_add_f32_e32 v208, v177, v208
	v_exp_f32_e32 v218, v218
	v_mfma_f32_32x32x16_bf16 v[64:79], v[68:71], v[118:121], 0
	v_add_f32_e32 v208, v163, v208
	v_exp_f32_e32 v219, v219
	v_add_f32_e32 v208, v176, v208
	v_exp_f32_e32 v220, v220
	v_add_f32_e32 v208, v164, v208
	s_waitcnt lgkmcnt(4)
	v_mfma_f32_32x32x16_bf16 v[80:95], v[232:235], v[114:117], v[80:95]
	ds_read_b128 v[232:235], v195 offset:32768
	v_exp_f32_e32 v221, v221
	v_add_f32_e32 v208, v175, v208
	v_exp_f32_e32 v210, v210
	v_add_f32_e32 v208, v165, v208
	v_mfma_f32_32x32x16_bf16 v[64:79], v[236:239], v[114:117], v[64:79]
	ds_read_b128 v[236:239], v195 offset:40960
	v_exp_f32_e32 v211, v211
	v_add_f32_e32 v208, v174, v208
	v_exp_f32_e32 v212, v212
	v_add_f32_e32 v208, v166, v208
	s_waitcnt lgkmcnt(4)
	v_mfma_f32_32x32x16_bf16 v[80:95], v[250:253], v[126:129], v[80:95]
	ds_read_b128 v[250:253], v193 offset:32768
	v_exp_f32_e32 v213, v213
	v_add_f32_e32 v208, v173, v208
	v_exp_f32_e32 v214, v214
	v_add_f32_e32 v208, v167, v208
	v_mfma_f32_32x32x16_bf16 v[64:79], v[244:247], v[126:129], v[64:79]
	ds_read_b128 v[244:247], v193 offset:40960
	v_exp_f32_e32 v215, v215
	v_add_f32_e32 v208, v172, v208
	v_exp_f32_e32 v216, v216
	v_add_f32_e32 v208, v168, v208
	s_waitcnt lgkmcnt(4)
	v_mfma_f32_32x32x16_bf16 v[80:95], v[224:227], v[122:125], v[80:95]
	ds_read_b128 v[224:227], v202 offset:32768
	v_exp_f32_e32 v222, v222
	v_add_f32_e32 v208, v171, v208
	v_exp_f32_e32 v223, v223
	v_add_f32_e32 v208, v169, v208
	v_mfma_f32_32x32x16_bf16 v[64:79], v[228:231], v[122:125], v[64:79]
	ds_read_b128 v[228:231], v202 offset:40960
	v_add_f32_e32 v208, v170, v208
	v_add_f32_e32 v208, v217, v208
	v_add_f32_e32 v208, v218, v208
	v_add_f32_e32 v208, v219, v208
	s_waitcnt lgkmcnt(4)
	v_mfma_f32_32x32x16_bf16 v[80:95], v[232:235], v[110:113], v[80:95]
	ds_read_b128 v[232:235], v201 offset:32768
	v_add_f32_e32 v208, v220, v208
	v_add_f32_e32 v208, v221, v208
	v_add_f32_e32 v208, v210, v208
	v_add_f32_e32 v208, v211, v208
	v_mfma_f32_32x32x16_bf16 v[64:79], v[236:239], v[110:113], v[64:79]
	ds_read_b128 v[236:239], v201 offset:40960
	v_add_f32_e32 v208, v212, v208
	v_add_f32_e32 v208, v213, v208
	v_add_f32_e32 v208, v214, v208
	v_add_f32_e32 v208, v215, v208
	s_waitcnt lgkmcnt(4)
	v_mfma_f32_32x32x16_bf16 v[80:95], v[250:253], v[106:109], v[80:95]
	v_add_f32_e32 v208, v216, v208
	v_add_f32_e32 v208, v249, v208
	v_add_f32_e32 v208, v222, v208
	v_add_f32_e32 v208, v223, v208
	v_mfma_f32_32x32x16_bf16 v[64:79], v[244:247], v[106:109], v[64:79]
	v_add_f32_e32 v208, v248, v208
	v_mov_b32_e32 v209, v208
	v_cvt_pk_bf16_f32 v162, v162, v177
	v_cvt_pk_bf16_f32 v163, v163, v176
	s_waitcnt lgkmcnt(2)
	v_mfma_f32_32x32x16_bf16 v[80:95], v[224:227], v[102:105], v[80:95]
	v_cvt_pk_bf16_f32 v164, v164, v175
	v_cvt_pk_bf16_f32 v165, v165, v174
	v_cvt_pk_bf16_f32 v166, v166, v173
	v_cvt_pk_bf16_f32 v167, v167, v172
	v_mfma_f32_32x32x16_bf16 v[64:79], v[228:231], v[102:105], v[64:79]
	v_cvt_pk_bf16_f32 v168, v168, v171
	v_cvt_pk_bf16_f32 v169, v169, v170
	v_cvt_pk_bf16_f32 v170, v217, v218
	v_cvt_pk_bf16_f32 v171, v219, v220
	s_waitcnt lgkmcnt(0)
	v_mfma_f32_32x32x16_bf16 v[80:95], v[232:235], v[98:101], v[80:95]
	v_cvt_pk_bf16_f32 v172, v221, v210
	v_cvt_pk_bf16_f32 v173, v211, v212
	v_cvt_pk_bf16_f32 v174, v213, v214
	v_cvt_pk_bf16_f32 v175, v215, v216
	v_mfma_f32_32x32x16_bf16 v[64:79], v[236:239], v[98:101], v[64:79]
	v_cvt_pk_bf16_f32 v176, v249, v222
	v_cvt_pk_bf16_f32 v177, v223, v248
	ds_read_b64_tr_b16 v[210:211], v186 offset:0x0
	ds_read_b64_tr_b16 v[212:213], v186 offset:0x800
	ds_read_b64_tr_b16 v[214:215], v186 offset:0x200
	ds_read_b64_tr_b16 v[216:217], v186 offset:0xa00
	ds_read_b64_tr_b16 v[218:219], v186 offset:0x400
	ds_read_b64_tr_b16 v[220:221], v186 offset:0xc00
	ds_read_b64_tr_b16 v[222:223], v186 offset:0x600
	ds_read_b64_tr_b16 v[224:225], v186 offset:0xe00
	s_nop 1
	v_permlane32_swap_b32_e32 v208, v209
	s_waitcnt vmcnt(1)
	ds_write_b128 v188, v[154:157] offset:49152
	s_waitcnt vmcnt(0)
	ds_write_b128 v189, v[158:161] offset:49152
	s_cmp_ge_u32 s34, s35
	s_cselect_b64 s[6:7], -1, 0
	s_cbranch_scc1 .LBB0_532
	global_load_dwordx4 v[130:133], v178, s[66:67]
	global_load_dwordx4 v[134:137], v178, s[98:99]
	global_load_dwordx4 v[138:141], v179, s[66:67]
	global_load_dwordx4 v[142:145], v179, s[98:99]
	s_add_u32 s66, s66, 0x4000
	s_addc_u32 s67, s67, 0
	s_add_u32 s98, s98, 0x4000
	s_addc_u32 s99, s99, 0

.LBB0_538:
	ds_read_b128 v[64:67], v192 offset:49152
	ds_read_b128 v[68:71], v192 offset:57344
	s_waitcnt lgkmcnt(1)
	v_mfma_f32_32x32x16_bf16 v[80:95], v[64:67], v[118:121], 0
	s_waitcnt lgkmcnt(0)
	v_mfma_f32_32x32x16_bf16 v[64:79], v[68:71], v[118:121], 0
	ds_read_b128 v[118:121], v200 offset:49152
	ds_read_b128 v[130:133], v200 offset:57344
	s_waitcnt lgkmcnt(1)
	v_mfma_f32_32x32x16_bf16 v[80:95], v[118:121], v[114:117], v[80:95]
	s_waitcnt lgkmcnt(0)
	v_mfma_f32_32x32x16_bf16 v[64:79], v[130:133], v[114:117], v[64:79]
	ds_read_b128 v[114:117], v199 offset:49152
	ds_read_b128 v[118:121], v199 offset:57344
	s_waitcnt lgkmcnt(1)
	v_mfma_f32_32x32x16_bf16 v[80:95], v[114:117], v[126:129], v[80:95]
	s_waitcnt lgkmcnt(0)
	v_mfma_f32_32x32x16_bf16 v[64:79], v[118:121], v[126:129], v[64:79]
	ds_read_b128 v[114:117], v198 offset:49152
	ds_read_b128 v[118:121], v198 offset:57344
	s_waitcnt lgkmcnt(1)
	v_mfma_f32_32x32x16_bf16 v[80:95], v[114:117], v[122:125], v[80:95]
	s_waitcnt lgkmcnt(0)
	v_mfma_f32_32x32x16_bf16 v[64:79], v[118:121], v[122:125], v[64:79]
	ds_read_b128 v[114:117], v195 offset:49152
	ds_read_b128 v[118:121], v195 offset:57344
	v_exp_f32_e32 v122, v146
	v_exp_f32_e32 v123, v147
	s_waitcnt lgkmcnt(1)
	v_mfma_f32_32x32x16_bf16 v[80:95], v[114:117], v[110:113], v[80:95]
	s_waitcnt lgkmcnt(0)
	v_mfma_f32_32x32x16_bf16 v[64:79], v[118:121], v[110:113], v[64:79]
	ds_read_b128 v[110:113], v193 offset:49152
	ds_read_b128 v[114:117], v193 offset:57344
	v_exp_f32_e32 v118, v156
	v_exp_f32_e32 v119, v157
	v_exp_f32_e32 v120, v152
	v_exp_f32_e32 v121, v153
	s_waitcnt lgkmcnt(1)
	v_mfma_f32_32x32x16_bf16 v[80:95], v[110:113], v[106:109], v[80:95]
	s_waitcnt lgkmcnt(0)
	v_mfma_f32_32x32x16_bf16 v[64:79], v[114:117], v[106:109], v[64:79]
	ds_read_b128 v[106:109], v202 offset:49152
	ds_read_b128 v[110:113], v202 offset:57344
	v_exp_f32_e32 v114, v150
	v_exp_f32_e32 v115, v151
	v_exp_f32_e32 v116, v148
	v_exp_f32_e32 v117, v149
	s_waitcnt lgkmcnt(1)
	v_mfma_f32_32x32x16_bf16 v[80:95], v[106:109], v[102:105], v[80:95]
	s_waitcnt lgkmcnt(0)
	v_mfma_f32_32x32x16_bf16 v[64:79], v[110:113], v[102:105], v[64:79]
	ds_read_b128 v[102:105], v201 offset:49152
	ds_read_b128 v[106:109], v201 offset:57344
	v_exp_f32_e32 v110, v158
	v_exp_f32_e32 v111, v159
	v_exp_f32_e32 v112, v154
	v_exp_f32_e32 v113, v155
	s_waitcnt lgkmcnt(1)
	v_mfma_f32_32x32x16_bf16 v[80:95], v[102:105], v[98:101], v[80:95]
	s_waitcnt lgkmcnt(0)
	v_mfma_f32_32x32x16_bf16 v[64:79], v[106:109], v[98:101], v[64:79]
	v_add_f32_e32 v98, 0, v163
	v_add_f32_e32 v98, v177, v98
	v_add_f32_e32 v98, v164, v98
	v_add_f32_e32 v98, v207, v98
	v_add_f32_e32 v98, v176, v98
	v_add_f32_e32 v98, v210, v98
	v_add_f32_e32 v98, v165, v98
	v_add_f32_e32 v98, v175, v98
	v_add_f32_e32 v98, v166, v98
	v_add_f32_e32 v98, v173, v98
	v_add_f32_e32 v98, v167, v98
	v_add_f32_e32 v98, v174, v98
	v_exp_f32_e32 v108, v160
	v_add_f32_e32 v98, v168, v98
	v_exp_f32_e32 v109, v161
	v_add_f32_e32 v98, v171, v98
	v_add_f32_e32 v98, v169, v98
	v_add_f32_e32 v98, v172, v98
	v_add_f32_e32 v98, v108, v98
	v_add_f32_e32 v98, v109, v98
	v_add_f32_e32 v98, v110, v98
	v_add_f32_e32 v98, v111, v98
	v_add_f32_e32 v98, v112, v98
	v_add_f32_e32 v98, v113, v98
	v_add_f32_e32 v98, v114, v98
	v_add_f32_e32 v98, v115, v98
	v_add_f32_e32 v98, v116, v98
	v_add_f32_e32 v98, v117, v98
	v_add_f32_e32 v98, v118, v98
	v_add_f32_e32 v98, v119, v98
	v_add_f32_e32 v98, v120, v98
	v_add_f32_e32 v98, v121, v98
	v_add_f32_e32 v98, v122, v98
	v_add_f32_e32 v98, v123, v98
	v_mov_b32_e32 v99, v98
	v_cvt_pk_bf16_f32 v100, v163, v177
	v_cvt_pk_bf16_f32 v101, v164, v207
	v_cvt_pk_bf16_f32 v102, v176, v210
	v_cvt_pk_bf16_f32 v103, v165, v175
	s_nop 1
	v_permlane32_swap_b32_e32 v98, v99
	v_cvt_pk_bf16_f32 v104, v166, v173
	v_cvt_pk_bf16_f32 v105, v167, v174
	v_cvt_pk_bf16_f32 v106, v168, v171
	v_cvt_pk_bf16_f32 v107, v169, v172
	v_cvt_pk_bf16_f32 v108, v108, v109
	v_cvt_pk_bf16_f32 v109, v110, v111
	v_cvt_pk_bf16_f32 v110, v112, v113
	v_cvt_pk_bf16_f32 v111, v114, v115
	v_cvt_pk_bf16_f32 v112, v116, v117
	v_cvt_pk_bf16_f32 v113, v118, v119
	v_cvt_pk_bf16_f32 v114, v120, v121
	v_cvt_pk_bf16_f32 v115, v122, v123
	s_nop 0
	ds_read_b64_tr_b16 v[116:117], v187 offset:0
	ds_read_b64_tr_b16 v[118:119], v187 offset:0x800
	ds_read_b64_tr_b16 v[120:121], v187 offset:0x1000
	ds_read_b64_tr_b16 v[122:123], v187 offset:0x1800
	ds_read_b64_tr_b16 v[124:125], v187 offset:0x2000
	ds_read_b64_tr_b16 v[126:127], v187 offset:0x2800
	ds_read_b64_tr_b16 v[128:129], v187 offset:0x3000
	ds_read_b64_tr_b16 v[130:131], v187 offset:0x3800
	s_waitcnt lgkmcnt(0)
	s_nop 0
	v_mfma_f32_32x32x16_bf16 v[0:15], v[100:103], v[116:119], v[0:15]
	ds_read_b64_tr_b16 v[116:117], v187 offset:0x200
	ds_read_b64_tr_b16 v[118:119], v187 offset:0xa00
	v_mfma_f32_32x32x16_bf16 v[0:15], v[104:107], v[120:123], v[0:15]
	ds_read_b64_tr_b16 v[120:121], v187 offset:0x1200
	ds_read_b64_tr_b16 v[122:123], v187 offset:0x1a00
	v_mfma_f32_32x32x16_bf16 v[0:15], v[108:111], v[124:127], v[0:15]
	ds_read_b64_tr_b16 v[124:125], v187 offset:0x2200
	ds_read_b64_tr_b16 v[126:127], v187 offset:0x2a00
	v_mfma_f32_32x32x16_bf16 v[0:15], v[112:115], v[128:131], v[0:15]
	ds_read_b64_tr_b16 v[128:129], v187 offset:0x3200
	ds_read_b64_tr_b16 v[130:131], v187 offset:0x3a00
	s_waitcnt lgkmcnt(0)
	v_mfma_f32_32x32x16_bf16 v[48:63], v[100:103], v[116:119], v[48:63]
	ds_read_b64_tr_b16 v[116:117], v187 offset:0x400
	ds_read_b64_tr_b16 v[118:119], v187 offset:0xc00
	v_mfma_f32_32x32x16_bf16 v[48:63], v[104:107], v[120:123], v[48:63]
	ds_read_b64_tr_b16 v[120:121], v187 offset:0x1400
	ds_read_b64_tr_b16 v[122:123], v187 offset:0x1c00
	v_mfma_f32_32x32x16_bf16 v[48:63], v[108:111], v[124:127], v[48:63]
	ds_read_b64_tr_b16 v[124:125], v187 offset:0x2400
	ds_read_b64_tr_b16 v[126:127], v187 offset:0x2c00
	v_mfma_f32_32x32x16_bf16 v[48:63], v[112:115], v[128:131], v[48:63]
	ds_read_b64_tr_b16 v[128:129], v187 offset:0x3400
	ds_read_b64_tr_b16 v[130:131], v187 offset:0x3c00
	s_waitcnt lgkmcnt(0)
	v_mfma_f32_32x32x16_bf16 v[32:47], v[100:103], v[116:119], v[32:47]
	ds_read_b64_tr_b16 v[116:117], v187 offset:0x600
	ds_read_b64_tr_b16 v[118:119], v187 offset:0xe00
	v_mfma_f32_32x32x16_bf16 v[32:47], v[104:107], v[120:123], v[32:47]
	ds_read_b64_tr_b16 v[120:121], v187 offset:0x1600
	ds_read_b64_tr_b16 v[122:123], v187 offset:0x1e00
	v_mfma_f32_32x32x16_bf16 v[32:47], v[108:111], v[124:127], v[32:47]
	ds_read_b64_tr_b16 v[124:125], v187 offset:0x2600
	ds_read_b64_tr_b16 v[126:127], v187 offset:0x2e00
	v_mfma_f32_32x32x16_bf16 v[32:47], v[112:115], v[128:131], v[32:47]
	ds_read_b64_tr_b16 v[128:129], v187 offset:0x3600
	ds_read_b64_tr_b16 v[130:131], v187 offset:0x3e00
	s_waitcnt lgkmcnt(0)
	v_mfma_f32_32x32x16_bf16 v[16:31], v[100:103], v[116:119], v[16:31]
	v_max_f32_e32 v100, v81, v81
	v_max_f32_e32 v101, v80, v80
	v_max_f32_e32 v100, v101, v100
	v_max3_f32 v100, v100, v82, v83
	v_max3_f32 v100, v100, v84, v85
	v_max3_f32 v100, v100, v86, v87
	v_max3_f32 v100, v100, v88, v89
	v_max3_f32 v100, v100, v90, v91
	v_max3_f32 v100, v100, v92, v93
	v_mfma_f32_32x32x16_bf16 v[16:31], v[104:107], v[120:123], v[16:31]
	v_max3_f32 v100, v100, v94, v95
	v_max3_f32 v100, v100, v64, v65
	v_max3_f32 v100, v100, v66, v67
	v_max3_f32 v100, v100, v68, v69
	v_max3_f32 v100, v100, v70, v71
	v_max3_f32 v100, v100, v72, v73
	v_max3_f32 v100, v100, v74, v75
	v_max3_f32 v100, v100, v76, v77
	v_mfma_f32_32x32x16_bf16 v[16:31], v[108:111], v[124:127], v[16:31]
	v_max3_f32 v100, v100, v78, v79
	v_mov_b32_e32 v101, v100
	s_nop 1
	v_permlane32_swap_b32_e32 v100, v101
	v_max_f32_e32 v101, v101, v101
	v_max_f32_e32 v100, v100, v100
	v_max_f32_e32 v100, v100, v101
	v_sub_f32_e32 v101, v100, v170
	v_cmp_ge_f32_e32 vcc, s92, v101
	v_max_f32_e32 v101, v170, v170
	v_max_f32_e32 v101, v101, v100
	v_mfma_f32_32x32x16_bf16 v[16:31], v[112:115], v[128:131], v[16:31]
	v_sub_f32_e32 v100, v170, v101
	v_mul_f32_e32 v100, 0x3e0293ee, v100
	v_exp_f32_e32 v100, v100
	s_cmp_eq_u64 vcc, exec
	s_cselect_b64 s[42:43], -1, 0
	v_cndmask_b32_e64 v100, v100, 1.0, s[42:43]
	v_cmp_gt_f32_e32 vcc, 1.0, v100
	s_barrier
	s_cbranch_vccz .LBB0_542
	s_and_saveexec_b64 s[6:7], s[40:41]
	ds_write_b32 v184, v100 offset:128
	s_or_b64 exec, exec, s[6:7]
	s_waitcnt lgkmcnt(0)
	ds_read_b128 v[102:105], v182 offset:224
	ds_read_b128 v[106:109], v182 offset:192
	ds_read_b128 v[110:113], v182 offset:160
	ds_read_b128 v[114:117], v182 offset:128
	s_waitcnt lgkmcnt(3)
	v_pk_mul_f32 v[14:15], v[14:15], v[104:105]
	s_waitcnt lgkmcnt(2)
	v_pk_mul_f32 v[10:11], v[10:11], v[108:109]
	s_waitcnt lgkmcnt(1)
	v_pk_mul_f32 v[6:7], v[6:7], v[112:113]
	s_waitcnt lgkmcnt(0)
	v_pk_mul_f32 v[2:3], v[2:3], v[116:117]
	v_pk_mul_f32 v[12:13], v[12:13], v[102:103]
	v_pk_mul_f32 v[8:9], v[8:9], v[106:107]
	v_pk_mul_f32 v[4:5], v[4:5], v[110:111]
	v_pk_mul_f32 v[0:1], v[0:1], v[114:115]
	v_pk_mul_f32 v[62:63], v[62:63], v[104:105]
	v_pk_mul_f32 v[58:59], v[58:59], v[108:109]
	v_pk_mul_f32 v[54:55], v[54:55], v[112:113]
	v_pk_mul_f32 v[50:51], v[50:51], v[116:117]
	v_pk_mul_f32 v[60:61], v[60:61], v[102:103]
	v_pk_mul_f32 v[56:57], v[56:57], v[106:107]
	v_pk_mul_f32 v[52:53], v[52:53], v[110:111]
	v_pk_mul_f32 v[48:49], v[48:49], v[114:115]
	v_pk_mul_f32 v[46:47], v[46:47], v[104:105]
	v_pk_mul_f32 v[42:43], v[42:43], v[108:109]
	v_pk_mul_f32 v[38:39], v[38:39], v[112:113]
	v_pk_mul_f32 v[34:35], v[34:35], v[116:117]
	v_pk_mul_f32 v[44:45], v[44:45], v[102:103]
	v_pk_mul_f32 v[40:41], v[40:41], v[106:107]
	v_pk_mul_f32 v[36:37], v[36:37], v[110:111]
	v_pk_mul_f32 v[32:33], v[32:33], v[114:115]
	v_pk_mul_f32 v[30:31], v[30:31], v[104:105]
	v_pk_mul_f32 v[26:27], v[26:27], v[108:109]
	v_pk_mul_f32 v[22:23], v[22:23], v[112:113]
	v_pk_mul_f32 v[18:19], v[18:19], v[116:117]
	v_pk_mul_f32 v[28:29], v[28:29], v[102:103]
	v_pk_mul_f32 v[24:25], v[24:25], v[106:107]
	v_pk_mul_f32 v[20:21], v[20:21], v[110:111]
	v_pk_mul_f32 v[16:17], v[16:17], v[114:115]
.LBB0_542:
	v_cndmask_b32_e64 v101, v101, v170, s[42:43]
	v_mul_f32_e32 v101, 0xbe0293ee, v101
	v_fmamk_f32 v80, v80, 0x3e0293ee, v101
	v_fmamk_f32 v81, v81, 0x3e0293ee, v101
	v_fmamk_f32 v102, v82, 0x3e0293ee, v101
	v_exp_f32_e32 v82, v80
	v_fmamk_f32 v103, v84, 0x3e0293ee, v101
	v_exp_f32_e32 v84, v81
	v_fmamk_f32 v83, v83, 0x3e0293ee, v101
	v_exp_f32_e32 v80, v102
	v_fmamk_f32 v64, v64, 0x3e0293ee, v101
	v_exp_f32_e32 v83, v83
	v_fmamk_f32 v104, v85, 0x3e0293ee, v101
	v_fmamk_f32 v113, v94, 0x3e0293ee, v101
	v_fmamk_f32 v94, v75, 0x3e0293ee, v101
	v_exp_f32_e32 v75, v103
	v_exp_f32_e32 v102, v64
	v_add_f32_e32 v64, 0, v82
	v_fmamk_f32 v105, v86, 0x3e0293ee, v101
	v_exp_f32_e32 v81, v104
	v_add_f32_e32 v64, v84, v64
	v_fmamk_f32 v106, v87, 0x3e0293ee, v101
	v_fmamk_f32 v112, v93, 0x3e0293ee, v101
	v_fmamk_f32 v93, v74, 0x3e0293ee, v101
	v_exp_f32_e32 v74, v105
	v_add_f32_e32 v64, v80, v64
	v_fmamk_f32 v107, v88, 0x3e0293ee, v101
	v_fmamk_f32 v114, v95, 0x3e0293ee, v101
	v_fmamk_f32 v95, v76, 0x3e0293ee, v101
	v_exp_f32_e32 v76, v106
	v_add_f32_e32 v64, v83, v64
	v_fmamk_f32 v108, v89, 0x3e0293ee, v101
	v_fmamk_f32 v109, v90, 0x3e0293ee, v101
	v_fmamk_f32 v90, v71, 0x3e0293ee, v101
	v_exp_f32_e32 v71, v107
	v_add_f32_e32 v64, v75, v64
	v_fmamk_f32 v111, v92, 0x3e0293ee, v101
	v_fmamk_f32 v92, v73, 0x3e0293ee, v101
	v_exp_f32_e32 v73, v108
	v_add_f32_e32 v64, v81, v64
	v_fmamk_f32 v110, v91, 0x3e0293ee, v101
	v_fmamk_f32 v88, v69, 0x3e0293ee, v101
	v_exp_f32_e32 v69, v109
	v_add_f32_e32 v64, v74, v64
	v_fmamk_f32 v91, v72, 0x3e0293ee, v101
	v_exp_f32_e32 v72, v110
	v_add_f32_e32 v64, v76, v64
	v_fmamk_f32 v86, v67, 0x3e0293ee, v101
	v_exp_f32_e32 v67, v111
	v_add_f32_e32 v64, v71, v64
	v_fmamk_f32 v89, v70, 0x3e0293ee, v101
	v_exp_f32_e32 v70, v112
	v_add_f32_e32 v64, v73, v64
	v_fmamk_f32 v85, v66, 0x3e0293ee, v101
	v_exp_f32_e32 v66, v113
	v_add_f32_e32 v64, v69, v64
	v_fmamk_f32 v87, v68, 0x3e0293ee, v101
	v_exp_f32_e32 v68, v114
	v_add_f32_e32 v64, v72, v64
	v_fmamk_f32 v65, v65, 0x3e0293ee, v101
	v_add_f32_e32 v64, v67, v64
	v_exp_f32_e32 v103, v65
	v_add_f32_e32 v64, v70, v64
	v_exp_f32_e32 v85, v85
	v_add_f32_e32 v64, v66, v64
	v_exp_f32_e32 v86, v86
	v_add_f32_e32 v64, v68, v64
	v_exp_f32_e32 v87, v87
	v_add_f32_e32 v64, v102, v64
	v_exp_f32_e32 v88, v88
	v_add_f32_e32 v64, v103, v64
	v_exp_f32_e32 v89, v89
	v_add_f32_e32 v64, v85, v64
	v_exp_f32_e32 v90, v90
	v_add_f32_e32 v64, v86, v64
	v_exp_f32_e32 v91, v91
	v_add_f32_e32 v64, v87, v64
	v_exp_f32_e32 v92, v92
	v_add_f32_e32 v64, v88, v64
	v_exp_f32_e32 v93, v93
	v_add_f32_e32 v64, v89, v64
	v_exp_f32_e32 v94, v94
	v_add_f32_e32 v64, v90, v64
	v_fmamk_f32 v77, v77, 0x3e0293ee, v101
	v_exp_f32_e32 v95, v95
	v_add_f32_e32 v64, v91, v64
	v_fmamk_f32 v78, v78, 0x3e0293ee, v101
	v_exp_f32_e32 v104, v77
	v_add_f32_e32 v64, v92, v64
	v_fmac_f32_e32 v101, 0x3e0293ee, v79
	v_exp_f32_e32 v105, v78
	v_add_f32_e32 v64, v93, v64
	v_exp_f32_e32 v101, v101
	v_add_f32_e32 v64, v94, v64
	v_add_f32_e32 v64, v95, v64
	v_add_f32_e32 v64, v104, v64
	v_add_f32_e32 v64, v105, v64
	v_add_f32_e32 v64, v101, v64
	v_mov_b32_e32 v65, v64
	s_nop 1
	v_permlane32_swap_b32_e32 v64, v65
	v_cvt_pk_bf16_f32 v78, v82, v84
	v_cvt_pk_bf16_f32 v79, v80, v83
	v_cvt_pk_bf16_f32 v80, v75, v81
	v_cvt_pk_bf16_f32 v81, v74, v76
	v_cvt_pk_bf16_f32 v74, v71, v73
	v_cvt_pk_bf16_f32 v75, v69, v72
	v_cvt_pk_bf16_f32 v76, v67, v70
	v_cvt_pk_bf16_f32 v77, v66, v68
	v_cvt_pk_bf16_f32 v66, v102, v103
	v_cvt_pk_bf16_f32 v67, v85, v86
	v_cvt_pk_bf16_f32 v68, v87, v88
	v_cvt_pk_bf16_f32 v69, v89, v90
	v_cvt_pk_bf16_f32 v70, v91, v92
	v_cvt_pk_bf16_f32 v71, v93, v94
	v_cvt_pk_bf16_f32 v72, v95, v104
	v_cvt_pk_bf16_f32 v73, v105, v101
	s_nop 0
	ds_read_b64_tr_b16 v[82:83], v186 offset:0
	ds_read_b64_tr_b16 v[84:85], v186 offset:0x800
	ds_read_b64_tr_b16 v[86:87], v186 offset:0x1000
	ds_read_b64_tr_b16 v[88:89], v186 offset:0x1800
	ds_read_b64_tr_b16 v[90:91], v186 offset:0x2000
	ds_read_b64_tr_b16 v[92:93], v186 offset:0x2800
	ds_read_b64_tr_b16 v[102:103], v186 offset:0x3000
	ds_read_b64_tr_b16 v[104:105], v186 offset:0x3800
	s_waitcnt lgkmcnt(0)
	s_nop 0
	v_mfma_f32_32x32x16_bf16 v[0:15], v[78:81], v[82:85], v[0:15]
	ds_read_b64_tr_b16 v[82:83], v186 offset:0x200
	ds_read_b64_tr_b16 v[84:85], v186 offset:0xa00
	v_mfma_f32_32x32x16_bf16 v[0:15], v[74:77], v[86:89], v[0:15]
	ds_read_b64_tr_b16 v[86:87], v186 offset:0x1200
	ds_read_b64_tr_b16 v[88:89], v186 offset:0x1a00
	v_mfma_f32_32x32x16_bf16 v[0:15], v[66:69], v[90:93], v[0:15]
	ds_read_b64_tr_b16 v[90:91], v186 offset:0x2200
	ds_read_b64_tr_b16 v[92:93], v186 offset:0x2a00
	v_mfma_f32_32x32x16_bf16 v[0:15], v[70:73], v[102:105], v[0:15]
	ds_read_b64_tr_b16 v[102:103], v186 offset:0x3200
	ds_read_b64_tr_b16 v[104:105], v186 offset:0x3a00
	s_waitcnt lgkmcnt(0)
	v_mfma_f32_32x32x16_bf16 v[48:63], v[78:81], v[82:85], v[48:63]
	ds_read_b64_tr_b16 v[82:83], v186 offset:0x400
	ds_read_b64_tr_b16 v[84:85], v186 offset:0xc00
	v_mfma_f32_32x32x16_bf16 v[48:63], v[74:77], v[86:89], v[48:63]
	ds_read_b64_tr_b16 v[86:87], v186 offset:0x1400
	ds_read_b64_tr_b16 v[88:89], v186 offset:0x1c00
	v_mfma_f32_32x32x16_bf16 v[48:63], v[66:69], v[90:93], v[48:63]
	ds_read_b64_tr_b16 v[90:91], v186 offset:0x2400
	ds_read_b64_tr_b16 v[92:93], v186 offset:0x2c00
	v_mfma_f32_32x32x16_bf16 v[48:63], v[70:73], v[102:105], v[48:63]
	ds_read_b64_tr_b16 v[102:103], v186 offset:0x3400
	ds_read_b64_tr_b16 v[104:105], v186 offset:0x3c00
	s_waitcnt lgkmcnt(0)
	v_mfma_f32_32x32x16_bf16 v[32:47], v[78:81], v[82:85], v[32:47]
	ds_read_b64_tr_b16 v[82:83], v186 offset:0x600
	ds_read_b64_tr_b16 v[84:85], v186 offset:0xe00
	v_mfma_f32_32x32x16_bf16 v[32:47], v[74:77], v[86:89], v[32:47]
	ds_read_b64_tr_b16 v[86:87], v186 offset:0x1600
	ds_read_b64_tr_b16 v[88:89], v186 offset:0x1e00
	v_mfma_f32_32x32x16_bf16 v[32:47], v[66:69], v[90:93], v[32:47]
	ds_read_b64_tr_b16 v[90:91], v186 offset:0x2600
	ds_read_b64_tr_b16 v[92:93], v186 offset:0x2e00
	v_mfma_f32_32x32x16_bf16 v[32:47], v[70:73], v[102:105], v[32:47]
	ds_read_b64_tr_b16 v[102:103], v186 offset:0x3600
	ds_read_b64_tr_b16 v[104:105], v186 offset:0x3e00
	s_waitcnt lgkmcnt(0)
	v_mfma_f32_32x32x16_bf16 v[16:31], v[78:81], v[82:85], v[16:31]
	v_mfma_f32_32x32x16_bf16 v[16:31], v[74:77], v[86:89], v[16:31]
	v_mfma_f32_32x32x16_bf16 v[16:31], v[66:69], v[90:93], v[16:31]
	v_mfma_f32_32x32x16_bf16 v[16:31], v[70:73], v[102:105], v[16:31]
	s_and_saveexec_b64 s[6:7], s[40:41]
	s_cbranch_execz .LBB0_519
	v_add_f32_e32 v66, v98, v99
	v_fmac_f32_e32 v66, v185, v162
	v_add_f32_e32 v64, v64, v65
	v_fmac_f32_e32 v64, v66, v100
	ds_write_b32 v184, v64
	s_branch .LBB0_519
